# v56 plus scalar-base form for the four K-loop LDS-DMA loads whose base is already scalar, and the no-op priority flips inside MFMA blocks removed
# speedup vs baseline: 1.0011x; 1.0011x over previous
; #define PG8_STAGE(bufoff, gbase, voff) do { _Pragma("unroll") for (int _i = 0; _i < 2; ++_i) \
;         __builtin_amdgcn_global_load_lds((const unsigned*)((const char*)(gbase) + (voff)[_i]), (PG8_LAS unsigned*)(lds + (bufoff) + ldsw + _i * 8192), 16, 0, 0); } while (0)
; #define PG8_LDA(dst, b, h) do { _Pragma("unroll") for (int m = 0; m < 4; ++m) _Pragma("unroll") for (int k = 0; k < 2; ++k) dst[m][k] = *(const PG8_LAS bf16x8*)(lds + PG8_SA(b, h) + aoff + m * 2048 + k * 1024); } while (0)
; #define PG8_LDB(dst, b, h) do { _Pragma("unroll") for (int n = 0; n < 2; ++n) _Pragma("unroll") for (int k = 0; k < 2; ++k) dst[n][k] = *(const PG8_LAS bf16x8*)(lds + PG8_SB(b, h) + boff + n * 2048 + k * 1024); } while (0)
; #define PG8_MMA(ai, bj, At, Bt) do { __builtin_amdgcn_s_setprio(1); _Pragma("unroll") for (int m = 0; m < 4; ++m) _Pragma("unroll") for (int n = 0; n < 2; ++n) _Pragma("unroll") for (int k = 0; k < 2; ++k) \
;         acc[ai][bj][m][n] = __builtin_amdgcn_mfma_f32_16x16x32_bf16(Bt[n][k], At[m][k], acc[ai][bj][m][n], 0, 0, 0); __builtin_amdgcn_s_setprio(0); } while (0)
; #define PG8_WAIT_V(n) asm volatile("s_waitcnt vmcnt(" #n ")" ::: "memory")
; #define PG8_WAIT_L(n) asm volatile("s_waitcnt lgkmcnt(" #n ")" ::: "memory")
; #define PG8_BAR __builtin_amdgcn_s_barrier()
; #define PG8_SCHED __builtin_amdgcn_sched_barrier(0)
; __device__ __forceinline__ void gemm_phase(PG8_LAS unsigned char* lds, const Gemm g, const StaticOrder& S, const Epi& E, const int tid) {
;     ...
;         for (int t = 0; t < nt; t += 2) {
;             const bool last = (t == nt - 2);
;             const char* a1 = cA + (size_t)(t + 1) * kstep;
;             const char* a2 = last ? nA : cA + (size_t)(t + 2) * kstep; const char* b2 = last ? nB : cB + (size_t)(t + 2) * kstep;
;             const char* a3 = a2 + kstep; const char* b3 = b2 + kstep;
;             PG8_LDB(B0, 0, 0); PG8_LDB(B1, 0, 1); PG8_SCHED; PG8_LDA(At, 0, 0); PG8_STAGE(PG8_SA(1, 1), a1 + hstepA, voffA);
;             PG8_WAIT_V(8); PG8_WAIT_L(0); PG8_BAR; PG8_MMA(0, 0, At, B0); PG8_MMA(0, 1, At, B1); PG8_BAR; PG8_SCHED;
;             PG8_LDA(At, 0, 1); PG8_STAGE(PG8_SB(0, 0), b2, voffB); PG8_STAGE(PG8_SB(0, 1), b2 + hstepB, voffB); PG8_STAGE(PG8_SA(0, 0), a2, voffA);
;             PG8_WAIT_V(8); PG8_WAIT_L(0); PG8_BAR; PG8_MMA(1, 0, At, B0); PG8_MMA(1, 1, At, B1); PG8_BAR; PG8_SCHED;
.LBB0_87:
	s_add_u32 s10, s10, 0x80
	s_addc_u32 s11, s11, 0
	s_add_u32 s47, s44, 0x100
	s_addc_u32 s48, s45, 0
	s_mov_b32 s44, 0
	s_add_i32 s49, s44, 2
	s_add_u32 s68, s10, 0x80
	s_addc_u32 s45, s11, 0
	s_add_i32 s78, 0, 0x10000
	s_cmp_eq_u32 s15, s44
	s_cselect_b32 s45, s5, s45
	s_cselect_b32 s44, s4, s68
	s_cselect_b32 s69, s39, s48
	s_cselect_b32 s68, s38, s47
	s_add_i32 s79, 0, 0x14000
	v_add_u32_e32 v160, s78, v186
	v_add_u32_e32 v189, s79, v186
	ds_read_b128 v[136:139], v160
	ds_read_b128 v[140:143], v160 offset:1024
	ds_read_b128 v[156:159], v160 offset:2048
	ds_read_b128 v[160:163], v160 offset:3072
	ds_read_b128 v[164:167], v189
	ds_read_b128 v[168:171], v189 offset:1024
	ds_read_b128 v[172:175], v189 offset:2048
	ds_read_b128 v[190:193], v189 offset:3072
	s_add_i32 m0, s3, 0xc000
	ds_read_b128 v[194:197], v188
	ds_read_b128 v[198:201], v188 offset:1024
	ds_read_b128 v[202:205], v188 offset:2048
	ds_read_b128 v[206:209], v188 offset:3072
	ds_read_b128 v[224:227], v188 offset:4096
	ds_read_b128 v[228:231], v188 offset:5120
	ds_read_b128 v[232:235], v188 offset:6144
	ds_read_b128 v[236:239], v188 offset:7168
	global_load_lds_dwordx4 v152, s[10:11]
	s_add_i32 m0, s3, 0xe000
	s_nop 0
	global_load_lds_dwordx4 v154, s[10:11]
	s_waitcnt vmcnt(8)
	s_waitcnt lgkmcnt(0)
	s_barrier
	s_setprio 1
	s_waitcnt lgkmcnt(0)
	v_mfma_f32_16x16x32_bf16 v[132:135], v[136:139], v[194:197], 0
	v_mfma_f32_16x16x32_bf16 v[128:131], v[156:159], v[194:197], 0
	v_mfma_f32_16x16x32_bf16 v[116:119], v[136:139], v[202:205], 0
	v_mfma_f32_16x16x32_bf16 v[106:109], v[156:159], v[202:205], 0
	v_mfma_f32_16x16x32_bf16 v[94:97], v[136:139], v[224:227], 0
	v_mfma_f32_16x16x32_bf16 v[90:93], v[156:159], v[224:227], 0
	v_mfma_f32_16x16x32_bf16 v[78:81], v[136:139], v[232:235], 0
	v_mfma_f32_16x16x32_bf16 v[74:77], v[156:159], v[232:235], 0
	v_mfma_f32_16x16x32_bf16 v[132:135], v[140:143], v[198:201], v[132:135]
	v_mfma_f32_16x16x32_bf16 v[128:131], v[160:163], v[198:201], v[128:131]
	v_mfma_f32_16x16x32_bf16 v[116:119], v[140:143], v[206:209], v[116:119]
	v_mfma_f32_16x16x32_bf16 v[106:109], v[160:163], v[206:209], v[106:109]
	v_mfma_f32_16x16x32_bf16 v[94:97], v[140:143], v[228:231], v[94:97]
	v_mfma_f32_16x16x32_bf16 v[90:93], v[160:163], v[228:231], v[90:93]
	v_mfma_f32_16x16x32_bf16 v[78:81], v[140:143], v[236:239], v[78:81]
	v_mfma_f32_16x16x32_bf16 v[74:77], v[160:163], v[236:239], v[74:77]
	v_mfma_f32_16x16x32_bf16 v[124:127], v[164:167], v[194:197], 0
	v_mfma_f32_16x16x32_bf16 v[120:123], v[172:175], v[194:197], 0
	v_mfma_f32_16x16x32_bf16 v[102:105], v[164:167], v[202:205], 0
	v_mfma_f32_16x16x32_bf16 v[98:101], v[172:175], v[202:205], 0
	v_mfma_f32_16x16x32_bf16 v[86:89], v[164:167], v[224:227], 0
	v_mfma_f32_16x16x32_bf16 v[82:85], v[172:175], v[224:227], 0
	v_mfma_f32_16x16x32_bf16 v[70:73], v[164:167], v[232:235], 0
	v_mfma_f32_16x16x32_bf16 v[66:69], v[172:175], v[232:235], 0
	v_mfma_f32_16x16x32_bf16 v[124:127], v[168:171], v[198:201], v[124:127]
	v_mfma_f32_16x16x32_bf16 v[120:123], v[190:193], v[198:201], v[120:123]
	v_mfma_f32_16x16x32_bf16 v[102:105], v[168:171], v[206:209], v[102:105]
	v_mfma_f32_16x16x32_bf16 v[98:101], v[190:193], v[206:209], v[98:101]
	v_mfma_f32_16x16x32_bf16 v[86:89], v[168:171], v[228:231], v[86:89]
	v_mfma_f32_16x16x32_bf16 v[82:85], v[190:193], v[228:231], v[82:85]
	v_mfma_f32_16x16x32_bf16 v[70:73], v[168:171], v[236:239], v[70:73]
	v_mfma_f32_16x16x32_bf16 v[66:69], v[190:193], v[236:239], v[66:69]
	s_setprio 0
	s_barrier
	s_add_i32 s78, s78, s31
	v_lshl_add_u64 v[210:211], s[68:69], 0, v[146:147]
	s_mov_b32 m0, s78
	ds_read_b128 v[194:197], v188 offset:16384
	ds_read_b128 v[198:201], v188 offset:17408
	ds_read_b128 v[202:205], v188 offset:18432
	ds_read_b128 v[206:209], v188 offset:19456
	ds_read_b128 v[224:227], v188 offset:20480
	ds_read_b128 v[228:231], v188 offset:21504
	ds_read_b128 v[232:235], v188 offset:22528
	ds_read_b128 v[236:239], v188 offset:23552
	global_load_lds_dwordx4 v[210:211], off
	s_add_i32 m0, s78, 0x2000
	v_lshl_add_u64 v[240:241], s[68:69], 0, v[150:151]
	s_add_u32 s68, s68, s34
	s_addc_u32 s69, s69, 0
	s_add_i32 s78, s79, s31
	global_load_lds_dwordx4 v[240:241], off
	v_lshl_add_u64 v[242:243], s[68:69], 0, v[146:147]
	s_mov_b32 m0, s78
	v_lshl_add_u64 v[244:245], s[68:69], 0, v[150:151]
	global_load_lds_dwordx4 v[242:243], off
	s_add_i32 m0, s78, 0x2000
	v_lshl_add_u64 v[246:247], s[44:45], 0, v[144:145]
	global_load_lds_dwordx4 v[244:245], off
	s_mov_b32 m0, s3
	v_lshl_add_u64 v[248:249], s[44:45], 0, v[148:149]
	global_load_lds_dwordx4 v[246:247], off
	s_mov_b32 m0, s17
	s_nop 0
	global_load_lds_dwordx4 v[248:249], off
	s_waitcnt vmcnt(8)
	s_waitcnt lgkmcnt(0)
	s_barrier
; #define PG8_STAGE(bufoff, gbase, voff) do { _Pragma("unroll") for (int _i = 0; _i < 2; ++_i) \
;         __builtin_amdgcn_global_load_lds((const unsigned*)((const char*)(gbase) + (voff)[_i]), (PG8_LAS unsigned*)(lds + (bufoff) + ldsw + _i * 8192), 16, 0, 0); } while (0)
; #define PG8_LDA(dst, b, h) do { _Pragma("unroll") for (int m = 0; m < 4; ++m) _Pragma("unroll") for (int k = 0; k < 2; ++k) dst[m][k] = *(const PG8_LAS bf16x8*)(lds + PG8_SA(b, h) + aoff + m * 2048 + k * 1024); } while (0)
; #define PG8_LDB(dst, b, h) do { _Pragma("unroll") for (int n = 0; n < 2; ++n) _Pragma("unroll") for (int k = 0; k < 2; ++k) dst[n][k] = *(const PG8_LAS bf16x8*)(lds + PG8_SB(b, h) + boff + n * 2048 + k * 1024); } while (0)
; #define PG8_MMA(ai, bj, At, Bt) do { __builtin_amdgcn_s_setprio(1); _Pragma("unroll") for (int m = 0; m < 4; ++m) _Pragma("unroll") for (int n = 0; n < 2; ++n) _Pragma("unroll") for (int k = 0; k < 2; ++k) \
;         acc[ai][bj][m][n] = __builtin_amdgcn_mfma_f32_16x16x32_bf16(Bt[n][k], At[m][k], acc[ai][bj][m][n], 0, 0, 0); __builtin_amdgcn_s_setprio(0); } while (0)
; #define PG8_WAIT_V(n) asm volatile("s_waitcnt vmcnt(" #n ")" ::: "memory")
; #define PG8_WAIT_L(n) asm volatile("s_waitcnt lgkmcnt(" #n ")" ::: "memory")
; #define PG8_BAR __builtin_amdgcn_s_barrier()
; #define PG8_SCHED __builtin_amdgcn_sched_barrier(0)
; __device__ __forceinline__ void gemm_phase(PG8_LAS unsigned char* lds, const Gemm g, const StaticOrder& S, const Epi& E, const int tid) {
;     ...
;             PG8_WAIT_V(8); PG8_WAIT_L(0); PG8_BAR; PG8_MMA(1, 0, At, B0); PG8_MMA(1, 1, At, B1); PG8_BAR; PG8_SCHED;
;             PG8_LDB(B0, 1, 0); PG8_LDB(B1, 1, 1); PG8_SCHED; PG8_LDA(At, 1, 0); PG8_STAGE(PG8_SA(0, 1), a2 + hstepA, voffA);
;             PG8_WAIT_V(8); PG8_WAIT_L(0); PG8_BAR; PG8_MMA(0, 0, At, B0); PG8_MMA(0, 1, At, B1); PG8_BAR; PG8_SCHED;
	s_setprio 1
	s_waitcnt lgkmcnt(0)
	v_mfma_f32_16x16x32_bf16 v[62:65], v[136:139], v[194:197], 0
	v_mfma_f32_16x16x32_bf16 v[58:61], v[156:159], v[194:197], 0
	v_mfma_f32_16x16x32_bf16 v[46:49], v[136:139], v[202:205], 0
	v_mfma_f32_16x16x32_bf16 v[42:45], v[156:159], v[202:205], 0
	v_mfma_f32_16x16x32_bf16 v[30:33], v[136:139], v[224:227], 0
	v_mfma_f32_16x16x32_bf16 v[26:29], v[156:159], v[224:227], 0
	v_mfma_f32_16x16x32_bf16 v[14:17], v[136:139], v[232:235], 0
	v_mfma_f32_16x16x32_bf16 v[10:13], v[156:159], v[232:235], 0
	v_mfma_f32_16x16x32_bf16 v[62:65], v[140:143], v[198:201], v[62:65]
	v_mfma_f32_16x16x32_bf16 v[58:61], v[160:163], v[198:201], v[58:61]
	v_mfma_f32_16x16x32_bf16 v[46:49], v[140:143], v[206:209], v[46:49]
	v_mfma_f32_16x16x32_bf16 v[42:45], v[160:163], v[206:209], v[42:45]
	v_mfma_f32_16x16x32_bf16 v[30:33], v[140:143], v[228:231], v[30:33]
	v_mfma_f32_16x16x32_bf16 v[26:29], v[160:163], v[228:231], v[26:29]
	v_mfma_f32_16x16x32_bf16 v[14:17], v[140:143], v[236:239], v[14:17]
	v_mfma_f32_16x16x32_bf16 v[10:13], v[160:163], v[236:239], v[10:13]
	v_mfma_f32_16x16x32_bf16 v[54:57], v[164:167], v[194:197], 0
	v_mfma_f32_16x16x32_bf16 v[50:53], v[172:175], v[194:197], 0
	v_mfma_f32_16x16x32_bf16 v[38:41], v[164:167], v[202:205], 0
	v_mfma_f32_16x16x32_bf16 v[34:37], v[172:175], v[202:205], 0
	v_mfma_f32_16x16x32_bf16 v[22:25], v[164:167], v[224:227], 0
	v_mfma_f32_16x16x32_bf16 v[18:21], v[172:175], v[224:227], 0
	v_mfma_f32_16x16x32_bf16 v[6:9], v[164:167], v[232:235], 0
	v_mfma_f32_16x16x32_bf16 v[2:5], v[172:175], v[232:235], 0
	v_mfma_f32_16x16x32_bf16 v[54:57], v[168:171], v[198:201], v[54:57]
	v_mfma_f32_16x16x32_bf16 v[50:53], v[190:193], v[198:201], v[50:53]
	v_mfma_f32_16x16x32_bf16 v[38:41], v[168:171], v[206:209], v[38:41]
	v_mfma_f32_16x16x32_bf16 v[34:37], v[190:193], v[206:209], v[34:37]
	v_mfma_f32_16x16x32_bf16 v[22:25], v[168:171], v[228:231], v[22:25]
	v_mfma_f32_16x16x32_bf16 v[18:21], v[190:193], v[228:231], v[18:21]
	v_mfma_f32_16x16x32_bf16 v[6:9], v[168:171], v[236:239], v[6:9]
	v_mfma_f32_16x16x32_bf16 v[2:5], v[190:193], v[236:239], v[2:5]
	s_setprio 0
	s_barrier
	s_add_i32 s68, 0, 0x18000
	s_add_i32 s69, 0, 0x1c000
	v_add_u32_e32 v160, s68, v186
	v_add_u32_e32 v189, s69, v186
	ds_read_b128 v[136:139], v160
	ds_read_b128 v[140:143], v160 offset:1024
	ds_read_b128 v[156:159], v160 offset:2048
	ds_read_b128 v[160:163], v160 offset:3072
	ds_read_b128 v[164:167], v189
	ds_read_b128 v[168:171], v189 offset:1024
	ds_read_b128 v[172:175], v189 offset:2048
	ds_read_b128 v[190:193], v189 offset:3072
	s_add_u32 s44, s44, s0
	s_addc_u32 s45, s45, 0
	s_mov_b32 m0, s58
	ds_read_b128 v[194:197], v188 offset:32768
	ds_read_b128 v[198:201], v188 offset:33792
	ds_read_b128 v[202:205], v188 offset:34816
	ds_read_b128 v[206:209], v188 offset:35840
	ds_read_b128 v[224:227], v188 offset:36864
	ds_read_b128 v[228:231], v188 offset:37888
	ds_read_b128 v[232:235], v188 offset:38912
	ds_read_b128 v[236:239], v188 offset:39936
	global_load_lds_dwordx4 v144, s[44:45]
	s_mov_b32 m0, s59
	s_nop 0
	global_load_lds_dwordx4 v148, s[44:45]
	s_waitcnt vmcnt(8)
	s_waitcnt lgkmcnt(0)
	s_barrier
	s_setprio 1
	s_waitcnt lgkmcnt(0)
	v_mfma_f32_16x16x32_bf16 v[132:135], v[136:139], v[194:197], v[132:135]
	v_mfma_f32_16x16x32_bf16 v[128:131], v[156:159], v[194:197], v[128:131]
	v_mfma_f32_16x16x32_bf16 v[116:119], v[136:139], v[202:205], v[116:119]
	v_mfma_f32_16x16x32_bf16 v[106:109], v[156:159], v[202:205], v[106:109]
	v_mfma_f32_16x16x32_bf16 v[94:97], v[136:139], v[224:227], v[94:97]
	v_mfma_f32_16x16x32_bf16 v[90:93], v[156:159], v[224:227], v[90:93]
	v_mfma_f32_16x16x32_bf16 v[78:81], v[136:139], v[232:235], v[78:81]
	v_mfma_f32_16x16x32_bf16 v[74:77], v[156:159], v[232:235], v[74:77]
	v_mfma_f32_16x16x32_bf16 v[132:135], v[140:143], v[198:201], v[132:135]
	v_mfma_f32_16x16x32_bf16 v[128:131], v[160:163], v[198:201], v[128:131]
	v_mfma_f32_16x16x32_bf16 v[116:119], v[140:143], v[206:209], v[116:119]
	v_mfma_f32_16x16x32_bf16 v[106:109], v[160:163], v[206:209], v[106:109]
	v_mfma_f32_16x16x32_bf16 v[94:97], v[140:143], v[228:231], v[94:97]
	v_mfma_f32_16x16x32_bf16 v[90:93], v[160:163], v[228:231], v[90:93]
	v_mfma_f32_16x16x32_bf16 v[78:81], v[140:143], v[236:239], v[78:81]
	v_mfma_f32_16x16x32_bf16 v[74:77], v[160:163], v[236:239], v[74:77]
	v_mfma_f32_16x16x32_bf16 v[124:127], v[164:167], v[194:197], v[124:127]
	v_mfma_f32_16x16x32_bf16 v[120:123], v[172:175], v[194:197], v[120:123]
	v_mfma_f32_16x16x32_bf16 v[102:105], v[164:167], v[202:205], v[102:105]
	v_mfma_f32_16x16x32_bf16 v[98:101], v[172:175], v[202:205], v[98:101]
	v_mfma_f32_16x16x32_bf16 v[86:89], v[164:167], v[224:227], v[86:89]
	v_mfma_f32_16x16x32_bf16 v[82:85], v[172:175], v[224:227], v[82:85]
	v_mfma_f32_16x16x32_bf16 v[70:73], v[164:167], v[232:235], v[70:73]
	v_mfma_f32_16x16x32_bf16 v[66:69], v[172:175], v[232:235], v[66:69]
	v_mfma_f32_16x16x32_bf16 v[124:127], v[168:171], v[198:201], v[124:127]
	v_mfma_f32_16x16x32_bf16 v[120:123], v[190:193], v[198:201], v[120:123]
	v_mfma_f32_16x16x32_bf16 v[102:105], v[168:171], v[206:209], v[102:105]
	v_mfma_f32_16x16x32_bf16 v[98:101], v[190:193], v[206:209], v[98:101]
	v_mfma_f32_16x16x32_bf16 v[86:89], v[168:171], v[228:231], v[86:89]
	v_mfma_f32_16x16x32_bf16 v[82:85], v[190:193], v[228:231], v[82:85]
	v_mfma_f32_16x16x32_bf16 v[70:73], v[168:171], v[236:239], v[70:73]
	v_mfma_f32_16x16x32_bf16 v[66:69], v[190:193], v[236:239], v[66:69]
	s_setprio 0
	s_barrier
; #define PG8_STAGE(bufoff, gbase, voff) do { _Pragma("unroll") for (int _i = 0; _i < 2; ++_i) \
;         __builtin_amdgcn_global_load_lds((const unsigned*)((const char*)(gbase) + (voff)[_i]), (PG8_LAS unsigned*)(lds + (bufoff) + ldsw + _i * 8192), 16, 0, 0); } while (0)
; #define PG8_LDA(dst, b, h) do { _Pragma("unroll") for (int m = 0; m < 4; ++m) _Pragma("unroll") for (int k = 0; k < 2; ++k) dst[m][k] = *(const PG8_LAS bf16x8*)(lds + PG8_SA(b, h) + aoff + m * 2048 + k * 1024); } while (0)
; #define PG8_LDB(dst, b, h) do { _Pragma("unroll") for (int n = 0; n < 2; ++n) _Pragma("unroll") for (int k = 0; k < 2; ++k) dst[n][k] = *(const PG8_LAS bf16x8*)(lds + PG8_SB(b, h) + boff + n * 2048 + k * 1024); } while (0)
; #define PG8_MMA(ai, bj, At, Bt) do { __builtin_amdgcn_s_setprio(1); _Pragma("unroll") for (int m = 0; m < 4; ++m) _Pragma("unroll") for (int n = 0; n < 2; ++n) _Pragma("unroll") for (int k = 0; k < 2; ++k) \
;         acc[ai][bj][m][n] = __builtin_amdgcn_mfma_f32_16x16x32_bf16(Bt[n][k], At[m][k], acc[ai][bj][m][n], 0, 0, 0); __builtin_amdgcn_s_setprio(0); } while (0)
; #define PG8_WAIT_V(n) asm volatile("s_waitcnt vmcnt(" #n ")" ::: "memory")
; #define PG8_WAIT_L(n) asm volatile("s_waitcnt lgkmcnt(" #n ")" ::: "memory")
; #define PG8_BAR __builtin_amdgcn_s_barrier()
; #define PG8_SCHED __builtin_amdgcn_sched_barrier(0)
; __device__ __forceinline__ void gemm_phase(PG8_LAS unsigned char* lds, const Gemm g, const StaticOrder& S, const Epi& E, const int tid) {
;     ...
;         for (int t = 0; t < nt; t += 2) {
;             const bool last = (t == nt - 2);
;             const char* a1 = cA + (size_t)(t + 1) * kstep;
;             const char* a2 = last ? nA : cA + (size_t)(t + 2) * kstep; const char* b2 = last ? nB : cB + (size_t)(t + 2) * kstep;
;             const char* a3 = a2 + kstep; const char* b3 = b2 + kstep;
;             PG8_LDB(B0, 0, 0); PG8_LDB(B1, 0, 1); PG8_SCHED; PG8_LDA(At, 0, 0); PG8_STAGE(PG8_SA(1, 1), a1 + hstepA, voffA);
;             PG8_WAIT_V(8); PG8_WAIT_L(0); PG8_BAR; PG8_MMA(0, 0, At, B0); PG8_MMA(0, 1, At, B1); PG8_BAR; PG8_SCHED;
;     ...
;             PG8_LDA(At, 1, 1); PG8_STAGE(PG8_SB(1, 0), b3, voffB); PG8_STAGE(PG8_SB(1, 1), b3 + hstepB, voffB); PG8_STAGE(PG8_SA(1, 0), a3, voffA);
;             PG8_WAIT_V(8); PG8_WAIT_L(0); PG8_BAR; PG8_MMA(1, 0, At, B0); PG8_MMA(1, 1, At, B1); PG8_BAR; PG8_SCHED;
;         }
	s_add_i32 s44, s68, s31
	v_lshl_add_u64 v[210:211], v[210:211], 0, s[36:37]
	s_mov_b32 m0, s44
	ds_read_b128 v[194:197], v188 offset:49152
	ds_read_b128 v[198:201], v188 offset:50176
	ds_read_b128 v[202:205], v188 offset:51200
	ds_read_b128 v[206:209], v188 offset:52224
	ds_read_b128 v[224:227], v188 offset:53248
	ds_read_b128 v[228:231], v188 offset:54272
	ds_read_b128 v[232:235], v188 offset:55296
	ds_read_b128 v[236:239], v188 offset:56320
	global_load_lds_dwordx4 v[210:211], off
	v_lshl_add_u64 v[210:211], v[240:241], 0, s[36:37]
	s_add_i32 m0, s44, 0x2000
	s_add_i32 s44, s69, s31
	global_load_lds_dwordx4 v[210:211], off
	v_lshl_add_u64 v[210:211], v[242:243], 0, s[36:37]
	s_mov_b32 m0, s44
	s_nop 0
	global_load_lds_dwordx4 v[210:211], off
	v_lshl_add_u64 v[210:211], v[244:245], 0, s[36:37]
	s_add_i32 m0, s44, 0x2000
	s_nop 0
	global_load_lds_dwordx4 v[210:211], off
	v_lshl_add_u64 v[210:211], v[246:247], 0, s[36:37]
	s_mov_b32 m0, s12
	s_nop 0
	global_load_lds_dwordx4 v[210:211], off
	v_lshl_add_u64 v[210:211], v[248:249], 0, s[36:37]
	s_mov_b32 m0, s13
	s_nop 0
	global_load_lds_dwordx4 v[210:211], off
	s_waitcnt vmcnt(8)
	s_waitcnt lgkmcnt(0)
	s_barrier
	s_setprio 1
	s_waitcnt lgkmcnt(0)
	v_mfma_f32_16x16x32_bf16 v[62:65], v[136:139], v[194:197], v[62:65]
	v_mfma_f32_16x16x32_bf16 v[58:61], v[156:159], v[194:197], v[58:61]
	v_mfma_f32_16x16x32_bf16 v[46:49], v[136:139], v[202:205], v[46:49]
	v_mfma_f32_16x16x32_bf16 v[42:45], v[156:159], v[202:205], v[42:45]
	v_mfma_f32_16x16x32_bf16 v[30:33], v[136:139], v[224:227], v[30:33]
	v_mfma_f32_16x16x32_bf16 v[26:29], v[156:159], v[224:227], v[26:29]
	v_mfma_f32_16x16x32_bf16 v[14:17], v[136:139], v[232:235], v[14:17]
	v_mfma_f32_16x16x32_bf16 v[10:13], v[156:159], v[232:235], v[10:13]
	v_mfma_f32_16x16x32_bf16 v[62:65], v[140:143], v[198:201], v[62:65]
	v_mfma_f32_16x16x32_bf16 v[58:61], v[160:163], v[198:201], v[58:61]
	v_mfma_f32_16x16x32_bf16 v[46:49], v[140:143], v[206:209], v[46:49]
	v_mfma_f32_16x16x32_bf16 v[42:45], v[160:163], v[206:209], v[42:45]
	v_mfma_f32_16x16x32_bf16 v[30:33], v[140:143], v[228:231], v[30:33]
	v_mfma_f32_16x16x32_bf16 v[26:29], v[160:163], v[228:231], v[26:29]
	v_mfma_f32_16x16x32_bf16 v[14:17], v[140:143], v[236:239], v[14:17]
	v_mfma_f32_16x16x32_bf16 v[10:13], v[160:163], v[236:239], v[10:13]
	v_mfma_f32_16x16x32_bf16 v[54:57], v[164:167], v[194:197], v[54:57]
	v_mfma_f32_16x16x32_bf16 v[50:53], v[172:175], v[194:197], v[50:53]
	v_mfma_f32_16x16x32_bf16 v[38:41], v[164:167], v[202:205], v[38:41]
	v_mfma_f32_16x16x32_bf16 v[34:37], v[172:175], v[202:205], v[34:37]
	v_mfma_f32_16x16x32_bf16 v[22:25], v[164:167], v[224:227], v[22:25]
	v_mfma_f32_16x16x32_bf16 v[18:21], v[172:175], v[224:227], v[18:21]
	v_mfma_f32_16x16x32_bf16 v[6:9], v[164:167], v[232:235], v[6:9]
	v_mfma_f32_16x16x32_bf16 v[2:5], v[172:175], v[232:235], v[2:5]
	v_mfma_f32_16x16x32_bf16 v[54:57], v[168:171], v[198:201], v[54:57]
	v_mfma_f32_16x16x32_bf16 v[50:53], v[190:193], v[198:201], v[50:53]
	v_mfma_f32_16x16x32_bf16 v[38:41], v[168:171], v[206:209], v[38:41]
	v_mfma_f32_16x16x32_bf16 v[34:37], v[190:193], v[206:209], v[34:37]
	v_mfma_f32_16x16x32_bf16 v[22:25], v[168:171], v[228:231], v[22:25]
	v_mfma_f32_16x16x32_bf16 v[18:21], v[190:193], v[228:231], v[18:21]
	v_mfma_f32_16x16x32_bf16 v[6:9], v[168:171], v[236:239], v[6:9]
	v_mfma_f32_16x16x32_bf16 v[2:5], v[190:193], v[236:239], v[2:5]
	s_setprio 0
	s_barrier
	s_add_u32 s10, s10, 0x100
	s_addc_u32 s11, s11, 0
	s_add_u32 s47, s47, 0x100
	s_addc_u32 s48, s48, 0
	s_cmp_ge_u32 s49, s14
	s_mov_b32 s44, s49
	s_cbranch_scc1 .Lk_peel_done
	.p2align 6
.LBB0_88:
	s_add_i32 s49, s44, 2
	s_add_u32 s68, s10, 0x80
	s_addc_u32 s45, s11, 0
	s_add_i32 s78, 0, 0x10000
	s_cmp_eq_u32 s15, s44
	s_cselect_b32 s45, s5, s45
	s_cselect_b32 s44, s4, s68
	s_cselect_b32 s69, s39, s48
	s_cselect_b32 s68, s38, s47
	s_add_i32 s79, 0, 0x14000
	v_add_u32_e32 v160, s78, v186
	v_add_u32_e32 v189, s79, v186
	ds_read_b128 v[136:139], v160
	ds_read_b128 v[140:143], v160 offset:1024
	ds_read_b128 v[156:159], v160 offset:2048
	ds_read_b128 v[160:163], v160 offset:3072
	ds_read_b128 v[164:167], v189
	ds_read_b128 v[168:171], v189 offset:1024
	ds_read_b128 v[172:175], v189 offset:2048
	ds_read_b128 v[190:193], v189 offset:3072
	s_add_i32 m0, s3, 0xc000
	ds_read_b128 v[194:197], v188
	ds_read_b128 v[198:201], v188 offset:1024
	ds_read_b128 v[202:205], v188 offset:2048
	ds_read_b128 v[206:209], v188 offset:3072
	ds_read_b128 v[224:227], v188 offset:4096
	ds_read_b128 v[228:231], v188 offset:5120
	ds_read_b128 v[232:235], v188 offset:6144
	ds_read_b128 v[236:239], v188 offset:7168
	global_load_lds_dwordx4 v152, s[10:11]
	s_add_i32 m0, s3, 0xe000
	s_nop 0
	global_load_lds_dwordx4 v154, s[10:11]
	s_waitcnt vmcnt(8)
	s_waitcnt lgkmcnt(0)
	s_barrier
; #define PG8_STAGE(bufoff, gbase, voff) do { _Pragma("unroll") for (int _i = 0; _i < 2; ++_i) \
;         __builtin_amdgcn_global_load_lds((const unsigned*)((const char*)(gbase) + (voff)[_i]), (PG8_LAS unsigned*)(lds + (bufoff) + ldsw + _i * 8192), 16, 0, 0); } while (0)
; #define PG8_LDA(dst, b, h) do { _Pragma("unroll") for (int m = 0; m < 4; ++m) _Pragma("unroll") for (int k = 0; k < 2; ++k) dst[m][k] = *(const PG8_LAS bf16x8*)(lds + PG8_SA(b, h) + aoff + m * 2048 + k * 1024); } while (0)
; #define PG8_LDB(dst, b, h) do { _Pragma("unroll") for (int n = 0; n < 2; ++n) _Pragma("unroll") for (int k = 0; k < 2; ++k) dst[n][k] = *(const PG8_LAS bf16x8*)(lds + PG8_SB(b, h) + boff + n * 2048 + k * 1024); } while (0)
; #define PG8_MMA(ai, bj, At, Bt) do { __builtin_amdgcn_s_setprio(1); _Pragma("unroll") for (int m = 0; m < 4; ++m) _Pragma("unroll") for (int n = 0; n < 2; ++n) _Pragma("unroll") for (int k = 0; k < 2; ++k) \
;         acc[ai][bj][m][n] = __builtin_amdgcn_mfma_f32_16x16x32_bf16(Bt[n][k], At[m][k], acc[ai][bj][m][n], 0, 0, 0); __builtin_amdgcn_s_setprio(0); } while (0)
; #define PG8_WAIT_V(n) asm volatile("s_waitcnt vmcnt(" #n ")" ::: "memory")
; #define PG8_WAIT_L(n) asm volatile("s_waitcnt lgkmcnt(" #n ")" ::: "memory")
; #define PG8_BAR __builtin_amdgcn_s_barrier()
; #define PG8_SCHED __builtin_amdgcn_sched_barrier(0)
; __device__ __forceinline__ void gemm_phase(PG8_LAS unsigned char* lds, const Gemm g, const StaticOrder& S, const Epi& E, const int tid) {
;     ...
;             PG8_WAIT_V(8); PG8_WAIT_L(0); PG8_BAR; PG8_MMA(0, 0, At, B0); PG8_MMA(0, 1, At, B1); PG8_BAR; PG8_SCHED;
;             PG8_LDA(At, 0, 1); PG8_STAGE(PG8_SB(0, 0), b2, voffB); PG8_STAGE(PG8_SB(0, 1), b2 + hstepB, voffB); PG8_STAGE(PG8_SA(0, 0), a2, voffA);
;             PG8_WAIT_V(8); PG8_WAIT_L(0); PG8_BAR; PG8_MMA(1, 0, At, B0); PG8_MMA(1, 1, At, B1); PG8_BAR; PG8_SCHED;
;             PG8_LDB(B0, 1, 0); PG8_LDB(B1, 1, 1); PG8_SCHED; PG8_LDA(At, 1, 0); PG8_STAGE(PG8_SA(0, 1), a2 + hstepA, voffA);
;             PG8_WAIT_V(8); PG8_WAIT_L(0); PG8_BAR; PG8_MMA(0, 0, At, B0); PG8_MMA(0, 1, At, B1); PG8_BAR; PG8_SCHED;
	s_setprio 1
	s_waitcnt lgkmcnt(0)
	v_mfma_f32_16x16x32_bf16 v[132:135], v[136:139], v[194:197], v[132:135]
	v_mfma_f32_16x16x32_bf16 v[128:131], v[156:159], v[194:197], v[128:131]
	v_mfma_f32_16x16x32_bf16 v[116:119], v[136:139], v[202:205], v[116:119]
	v_mfma_f32_16x16x32_bf16 v[106:109], v[156:159], v[202:205], v[106:109]
	v_mfma_f32_16x16x32_bf16 v[94:97], v[136:139], v[224:227], v[94:97]
	v_mfma_f32_16x16x32_bf16 v[90:93], v[156:159], v[224:227], v[90:93]
	v_mfma_f32_16x16x32_bf16 v[78:81], v[136:139], v[232:235], v[78:81]
	v_mfma_f32_16x16x32_bf16 v[74:77], v[156:159], v[232:235], v[74:77]
	v_mfma_f32_16x16x32_bf16 v[132:135], v[140:143], v[198:201], v[132:135]
	v_mfma_f32_16x16x32_bf16 v[128:131], v[160:163], v[198:201], v[128:131]
	v_mfma_f32_16x16x32_bf16 v[116:119], v[140:143], v[206:209], v[116:119]
	v_mfma_f32_16x16x32_bf16 v[106:109], v[160:163], v[206:209], v[106:109]
	v_mfma_f32_16x16x32_bf16 v[94:97], v[140:143], v[228:231], v[94:97]
	v_mfma_f32_16x16x32_bf16 v[90:93], v[160:163], v[228:231], v[90:93]
	v_mfma_f32_16x16x32_bf16 v[78:81], v[140:143], v[236:239], v[78:81]
	v_mfma_f32_16x16x32_bf16 v[74:77], v[160:163], v[236:239], v[74:77]
	v_mfma_f32_16x16x32_bf16 v[124:127], v[164:167], v[194:197], v[124:127]
	v_mfma_f32_16x16x32_bf16 v[120:123], v[172:175], v[194:197], v[120:123]
	v_mfma_f32_16x16x32_bf16 v[102:105], v[164:167], v[202:205], v[102:105]
	v_mfma_f32_16x16x32_bf16 v[98:101], v[172:175], v[202:205], v[98:101]
	v_mfma_f32_16x16x32_bf16 v[86:89], v[164:167], v[224:227], v[86:89]
	v_mfma_f32_16x16x32_bf16 v[82:85], v[172:175], v[224:227], v[82:85]
	v_mfma_f32_16x16x32_bf16 v[70:73], v[164:167], v[232:235], v[70:73]
	v_mfma_f32_16x16x32_bf16 v[66:69], v[172:175], v[232:235], v[66:69]
	v_mfma_f32_16x16x32_bf16 v[124:127], v[168:171], v[198:201], v[124:127]
	v_mfma_f32_16x16x32_bf16 v[120:123], v[190:193], v[198:201], v[120:123]
	v_mfma_f32_16x16x32_bf16 v[102:105], v[168:171], v[206:209], v[102:105]
	v_mfma_f32_16x16x32_bf16 v[98:101], v[190:193], v[206:209], v[98:101]
	v_mfma_f32_16x16x32_bf16 v[86:89], v[168:171], v[228:231], v[86:89]
	v_mfma_f32_16x16x32_bf16 v[82:85], v[190:193], v[228:231], v[82:85]
	v_mfma_f32_16x16x32_bf16 v[70:73], v[168:171], v[236:239], v[70:73]
	v_mfma_f32_16x16x32_bf16 v[66:69], v[190:193], v[236:239], v[66:69]
	s_setprio 0
	s_barrier
	s_add_i32 s78, s78, s31
	v_lshl_add_u64 v[210:211], s[68:69], 0, v[146:147]
	s_mov_b32 m0, s78
	ds_read_b128 v[194:197], v188 offset:16384
	ds_read_b128 v[198:201], v188 offset:17408
	ds_read_b128 v[202:205], v188 offset:18432
	ds_read_b128 v[206:209], v188 offset:19456
	ds_read_b128 v[224:227], v188 offset:20480
	ds_read_b128 v[228:231], v188 offset:21504
	ds_read_b128 v[232:235], v188 offset:22528
	ds_read_b128 v[236:239], v188 offset:23552
	global_load_lds_dwordx4 v[210:211], off
	s_add_i32 m0, s78, 0x2000
	v_lshl_add_u64 v[240:241], s[68:69], 0, v[150:151]
	s_add_u32 s68, s68, s34
	s_addc_u32 s69, s69, 0
	s_add_i32 s78, s79, s31
	global_load_lds_dwordx4 v[240:241], off
	v_lshl_add_u64 v[242:243], s[68:69], 0, v[146:147]
	s_mov_b32 m0, s78
	v_lshl_add_u64 v[244:245], s[68:69], 0, v[150:151]
	global_load_lds_dwordx4 v[242:243], off
	s_add_i32 m0, s78, 0x2000
	v_lshl_add_u64 v[246:247], s[44:45], 0, v[144:145]
	global_load_lds_dwordx4 v[244:245], off
	s_mov_b32 m0, s3
	v_lshl_add_u64 v[248:249], s[44:45], 0, v[148:149]
	global_load_lds_dwordx4 v[246:247], off
	s_mov_b32 m0, s17
	s_nop 0
	global_load_lds_dwordx4 v[248:249], off
	s_waitcnt vmcnt(8)
	s_waitcnt lgkmcnt(0)
	s_barrier
	s_setprio 1
	s_waitcnt lgkmcnt(0)
	v_mfma_f32_16x16x32_bf16 v[62:65], v[136:139], v[194:197], v[62:65]
	v_mfma_f32_16x16x32_bf16 v[58:61], v[156:159], v[194:197], v[58:61]
	v_mfma_f32_16x16x32_bf16 v[46:49], v[136:139], v[202:205], v[46:49]
	v_mfma_f32_16x16x32_bf16 v[42:45], v[156:159], v[202:205], v[42:45]
	v_mfma_f32_16x16x32_bf16 v[30:33], v[136:139], v[224:227], v[30:33]
	v_mfma_f32_16x16x32_bf16 v[26:29], v[156:159], v[224:227], v[26:29]
	v_mfma_f32_16x16x32_bf16 v[14:17], v[136:139], v[232:235], v[14:17]
	v_mfma_f32_16x16x32_bf16 v[10:13], v[156:159], v[232:235], v[10:13]
	v_mfma_f32_16x16x32_bf16 v[62:65], v[140:143], v[198:201], v[62:65]
	v_mfma_f32_16x16x32_bf16 v[58:61], v[160:163], v[198:201], v[58:61]
	v_mfma_f32_16x16x32_bf16 v[46:49], v[140:143], v[206:209], v[46:49]
	v_mfma_f32_16x16x32_bf16 v[42:45], v[160:163], v[206:209], v[42:45]
	v_mfma_f32_16x16x32_bf16 v[30:33], v[140:143], v[228:231], v[30:33]
	v_mfma_f32_16x16x32_bf16 v[26:29], v[160:163], v[228:231], v[26:29]
	v_mfma_f32_16x16x32_bf16 v[14:17], v[140:143], v[236:239], v[14:17]
	v_mfma_f32_16x16x32_bf16 v[10:13], v[160:163], v[236:239], v[10:13]
	v_mfma_f32_16x16x32_bf16 v[54:57], v[164:167], v[194:197], v[54:57]
	v_mfma_f32_16x16x32_bf16 v[50:53], v[172:175], v[194:197], v[50:53]
	v_mfma_f32_16x16x32_bf16 v[38:41], v[164:167], v[202:205], v[38:41]
	v_mfma_f32_16x16x32_bf16 v[34:37], v[172:175], v[202:205], v[34:37]
	v_mfma_f32_16x16x32_bf16 v[22:25], v[164:167], v[224:227], v[22:25]
	v_mfma_f32_16x16x32_bf16 v[18:21], v[172:175], v[224:227], v[18:21]
	v_mfma_f32_16x16x32_bf16 v[6:9], v[164:167], v[232:235], v[6:9]
	v_mfma_f32_16x16x32_bf16 v[2:5], v[172:175], v[232:235], v[2:5]
	v_mfma_f32_16x16x32_bf16 v[54:57], v[168:171], v[198:201], v[54:57]
	v_mfma_f32_16x16x32_bf16 v[50:53], v[190:193], v[198:201], v[50:53]
	v_mfma_f32_16x16x32_bf16 v[38:41], v[168:171], v[206:209], v[38:41]
	v_mfma_f32_16x16x32_bf16 v[34:37], v[190:193], v[206:209], v[34:37]
	v_mfma_f32_16x16x32_bf16 v[22:25], v[168:171], v[228:231], v[22:25]
	v_mfma_f32_16x16x32_bf16 v[18:21], v[190:193], v[228:231], v[18:21]
	v_mfma_f32_16x16x32_bf16 v[6:9], v[168:171], v[236:239], v[6:9]
	v_mfma_f32_16x16x32_bf16 v[2:5], v[190:193], v[236:239], v[2:5]
	s_setprio 0
	s_barrier
; #define PG8_STAGE(bufoff, gbase, voff) do { _Pragma("unroll") for (int _i = 0; _i < 2; ++_i) \
;         __builtin_amdgcn_global_load_lds((const unsigned*)((const char*)(gbase) + (voff)[_i]), (PG8_LAS unsigned*)(lds + (bufoff) + ldsw + _i * 8192), 16, 0, 0); } while (0)
; #define PG8_LDA(dst, b, h) do { _Pragma("unroll") for (int m = 0; m < 4; ++m) _Pragma("unroll") for (int k = 0; k < 2; ++k) dst[m][k] = *(const PG8_LAS bf16x8*)(lds + PG8_SA(b, h) + aoff + m * 2048 + k * 1024); } while (0)
; #define PG8_LDB(dst, b, h) do { _Pragma("unroll") for (int n = 0; n < 2; ++n) _Pragma("unroll") for (int k = 0; k < 2; ++k) dst[n][k] = *(const PG8_LAS bf16x8*)(lds + PG8_SB(b, h) + boff + n * 2048 + k * 1024); } while (0)
; #define PG8_MMA(ai, bj, At, Bt) do { __builtin_amdgcn_s_setprio(1); _Pragma("unroll") for (int m = 0; m < 4; ++m) _Pragma("unroll") for (int n = 0; n < 2; ++n) _Pragma("unroll") for (int k = 0; k < 2; ++k) \
;         acc[ai][bj][m][n] = __builtin_amdgcn_mfma_f32_16x16x32_bf16(Bt[n][k], At[m][k], acc[ai][bj][m][n], 0, 0, 0); __builtin_amdgcn_s_setprio(0); } while (0)
; #define PG8_WAIT_V(n) asm volatile("s_waitcnt vmcnt(" #n ")" ::: "memory")
; #define PG8_WAIT_L(n) asm volatile("s_waitcnt lgkmcnt(" #n ")" ::: "memory")
; #define PG8_BAR __builtin_amdgcn_s_barrier()
; #define PG8_SCHED __builtin_amdgcn_sched_barrier(0)
; __device__ __forceinline__ void gemm_phase(PG8_LAS unsigned char* lds, const Gemm g, const StaticOrder& S, const Epi& E, const int tid) {
;     ...
;             PG8_LDB(B0, 1, 0); PG8_LDB(B1, 1, 1); PG8_SCHED; PG8_LDA(At, 1, 0); PG8_STAGE(PG8_SA(0, 1), a2 + hstepA, voffA);
;             PG8_WAIT_V(8); PG8_WAIT_L(0); PG8_BAR; PG8_MMA(0, 0, At, B0); PG8_MMA(0, 1, At, B1); PG8_BAR; PG8_SCHED;
;             PG8_LDA(At, 1, 1); PG8_STAGE(PG8_SB(1, 0), b3, voffB); PG8_STAGE(PG8_SB(1, 1), b3 + hstepB, voffB); PG8_STAGE(PG8_SA(1, 0), a3, voffA);
;             PG8_WAIT_V(8); PG8_WAIT_L(0); PG8_BAR; PG8_MMA(1, 0, At, B0); PG8_MMA(1, 1, At, B1); PG8_BAR; PG8_SCHED;
;         }
	s_add_i32 s68, 0, 0x18000
	s_add_i32 s69, 0, 0x1c000
	v_add_u32_e32 v160, s68, v186
	v_add_u32_e32 v189, s69, v186
	ds_read_b128 v[136:139], v160
	ds_read_b128 v[140:143], v160 offset:1024
	ds_read_b128 v[156:159], v160 offset:2048
	ds_read_b128 v[160:163], v160 offset:3072
	ds_read_b128 v[164:167], v189
	ds_read_b128 v[168:171], v189 offset:1024
	ds_read_b128 v[172:175], v189 offset:2048
	ds_read_b128 v[190:193], v189 offset:3072
	s_add_u32 s44, s44, s0
	s_addc_u32 s45, s45, 0
	s_mov_b32 m0, s58
	ds_read_b128 v[194:197], v188 offset:32768
	ds_read_b128 v[198:201], v188 offset:33792
	ds_read_b128 v[202:205], v188 offset:34816
	ds_read_b128 v[206:209], v188 offset:35840
	ds_read_b128 v[224:227], v188 offset:36864
	ds_read_b128 v[228:231], v188 offset:37888
	ds_read_b128 v[232:235], v188 offset:38912
	ds_read_b128 v[236:239], v188 offset:39936
	global_load_lds_dwordx4 v144, s[44:45]
	s_mov_b32 m0, s59
	s_nop 0
	global_load_lds_dwordx4 v148, s[44:45]
	s_waitcnt vmcnt(8)
	s_waitcnt lgkmcnt(0)
	s_barrier
	s_setprio 1
	s_waitcnt lgkmcnt(0)
	v_mfma_f32_16x16x32_bf16 v[132:135], v[136:139], v[194:197], v[132:135]
	v_mfma_f32_16x16x32_bf16 v[128:131], v[156:159], v[194:197], v[128:131]
	v_mfma_f32_16x16x32_bf16 v[116:119], v[136:139], v[202:205], v[116:119]
	v_mfma_f32_16x16x32_bf16 v[106:109], v[156:159], v[202:205], v[106:109]
	v_mfma_f32_16x16x32_bf16 v[94:97], v[136:139], v[224:227], v[94:97]
	v_mfma_f32_16x16x32_bf16 v[90:93], v[156:159], v[224:227], v[90:93]
	v_mfma_f32_16x16x32_bf16 v[78:81], v[136:139], v[232:235], v[78:81]
	v_mfma_f32_16x16x32_bf16 v[74:77], v[156:159], v[232:235], v[74:77]
	v_mfma_f32_16x16x32_bf16 v[132:135], v[140:143], v[198:201], v[132:135]
	v_mfma_f32_16x16x32_bf16 v[128:131], v[160:163], v[198:201], v[128:131]
	v_mfma_f32_16x16x32_bf16 v[116:119], v[140:143], v[206:209], v[116:119]
	v_mfma_f32_16x16x32_bf16 v[106:109], v[160:163], v[206:209], v[106:109]
	v_mfma_f32_16x16x32_bf16 v[94:97], v[140:143], v[228:231], v[94:97]
	v_mfma_f32_16x16x32_bf16 v[90:93], v[160:163], v[228:231], v[90:93]
	v_mfma_f32_16x16x32_bf16 v[78:81], v[140:143], v[236:239], v[78:81]
	v_mfma_f32_16x16x32_bf16 v[74:77], v[160:163], v[236:239], v[74:77]
	v_mfma_f32_16x16x32_bf16 v[124:127], v[164:167], v[194:197], v[124:127]
	v_mfma_f32_16x16x32_bf16 v[120:123], v[172:175], v[194:197], v[120:123]
	v_mfma_f32_16x16x32_bf16 v[102:105], v[164:167], v[202:205], v[102:105]
	v_mfma_f32_16x16x32_bf16 v[98:101], v[172:175], v[202:205], v[98:101]
	v_mfma_f32_16x16x32_bf16 v[86:89], v[164:167], v[224:227], v[86:89]
	v_mfma_f32_16x16x32_bf16 v[82:85], v[172:175], v[224:227], v[82:85]
	v_mfma_f32_16x16x32_bf16 v[70:73], v[164:167], v[232:235], v[70:73]
	v_mfma_f32_16x16x32_bf16 v[66:69], v[172:175], v[232:235], v[66:69]
	v_mfma_f32_16x16x32_bf16 v[124:127], v[168:171], v[198:201], v[124:127]
	v_mfma_f32_16x16x32_bf16 v[120:123], v[190:193], v[198:201], v[120:123]
	v_mfma_f32_16x16x32_bf16 v[102:105], v[168:171], v[206:209], v[102:105]
	v_mfma_f32_16x16x32_bf16 v[98:101], v[190:193], v[206:209], v[98:101]
	v_mfma_f32_16x16x32_bf16 v[86:89], v[168:171], v[228:231], v[86:89]
	v_mfma_f32_16x16x32_bf16 v[82:85], v[190:193], v[228:231], v[82:85]
	v_mfma_f32_16x16x32_bf16 v[70:73], v[168:171], v[236:239], v[70:73]
	v_mfma_f32_16x16x32_bf16 v[66:69], v[190:193], v[236:239], v[66:69]
	s_setprio 0
	s_barrier
	s_add_i32 s44, s68, s31
	v_lshl_add_u64 v[210:211], v[210:211], 0, s[36:37]
	s_mov_b32 m0, s44
	ds_read_b128 v[194:197], v188 offset:49152
	ds_read_b128 v[198:201], v188 offset:50176
	ds_read_b128 v[202:205], v188 offset:51200
	ds_read_b128 v[206:209], v188 offset:52224
	ds_read_b128 v[224:227], v188 offset:53248
	ds_read_b128 v[228:231], v188 offset:54272
	ds_read_b128 v[232:235], v188 offset:55296
	ds_read_b128 v[236:239], v188 offset:56320
	global_load_lds_dwordx4 v[210:211], off
	v_lshl_add_u64 v[210:211], v[240:241], 0, s[36:37]
	s_add_i32 m0, s44, 0x2000
	s_add_i32 s44, s69, s31
	global_load_lds_dwordx4 v[210:211], off
	v_lshl_add_u64 v[210:211], v[242:243], 0, s[36:37]
	s_mov_b32 m0, s44
	s_nop 0
	global_load_lds_dwordx4 v[210:211], off
	v_lshl_add_u64 v[210:211], v[244:245], 0, s[36:37]
	s_add_i32 m0, s44, 0x2000
	s_nop 0
	global_load_lds_dwordx4 v[210:211], off
	v_lshl_add_u64 v[210:211], v[246:247], 0, s[36:37]
	s_mov_b32 m0, s12
	s_nop 0
	global_load_lds_dwordx4 v[210:211], off
	v_lshl_add_u64 v[210:211], v[248:249], 0, s[36:37]
	s_mov_b32 m0, s13
	s_nop 0
	global_load_lds_dwordx4 v[210:211], off
	s_waitcnt vmcnt(8)
	s_waitcnt lgkmcnt(0)
	s_barrier
	s_setprio 1
	s_waitcnt lgkmcnt(0)
	v_mfma_f32_16x16x32_bf16 v[62:65], v[136:139], v[194:197], v[62:65]
	v_mfma_f32_16x16x32_bf16 v[58:61], v[156:159], v[194:197], v[58:61]
	v_mfma_f32_16x16x32_bf16 v[46:49], v[136:139], v[202:205], v[46:49]
	v_mfma_f32_16x16x32_bf16 v[42:45], v[156:159], v[202:205], v[42:45]
	v_mfma_f32_16x16x32_bf16 v[30:33], v[136:139], v[224:227], v[30:33]
	v_mfma_f32_16x16x32_bf16 v[26:29], v[156:159], v[224:227], v[26:29]
	v_mfma_f32_16x16x32_bf16 v[14:17], v[136:139], v[232:235], v[14:17]
	v_mfma_f32_16x16x32_bf16 v[10:13], v[156:159], v[232:235], v[10:13]
	v_mfma_f32_16x16x32_bf16 v[62:65], v[140:143], v[198:201], v[62:65]
	v_mfma_f32_16x16x32_bf16 v[58:61], v[160:163], v[198:201], v[58:61]
	v_mfma_f32_16x16x32_bf16 v[46:49], v[140:143], v[206:209], v[46:49]
	v_mfma_f32_16x16x32_bf16 v[42:45], v[160:163], v[206:209], v[42:45]
	v_mfma_f32_16x16x32_bf16 v[30:33], v[140:143], v[228:231], v[30:33]
	v_mfma_f32_16x16x32_bf16 v[26:29], v[160:163], v[228:231], v[26:29]
	v_mfma_f32_16x16x32_bf16 v[14:17], v[140:143], v[236:239], v[14:17]
	v_mfma_f32_16x16x32_bf16 v[10:13], v[160:163], v[236:239], v[10:13]
	v_mfma_f32_16x16x32_bf16 v[54:57], v[164:167], v[194:197], v[54:57]
	v_mfma_f32_16x16x32_bf16 v[50:53], v[172:175], v[194:197], v[50:53]
	v_mfma_f32_16x16x32_bf16 v[38:41], v[164:167], v[202:205], v[38:41]
	v_mfma_f32_16x16x32_bf16 v[34:37], v[172:175], v[202:205], v[34:37]
	v_mfma_f32_16x16x32_bf16 v[22:25], v[164:167], v[224:227], v[22:25]
	v_mfma_f32_16x16x32_bf16 v[18:21], v[172:175], v[224:227], v[18:21]
	v_mfma_f32_16x16x32_bf16 v[6:9], v[164:167], v[232:235], v[6:9]
	v_mfma_f32_16x16x32_bf16 v[2:5], v[172:175], v[232:235], v[2:5]
	v_mfma_f32_16x16x32_bf16 v[54:57], v[168:171], v[198:201], v[54:57]
	v_mfma_f32_16x16x32_bf16 v[50:53], v[190:193], v[198:201], v[50:53]
	v_mfma_f32_16x16x32_bf16 v[38:41], v[168:171], v[206:209], v[38:41]
	v_mfma_f32_16x16x32_bf16 v[34:37], v[190:193], v[206:209], v[34:37]
	v_mfma_f32_16x16x32_bf16 v[22:25], v[168:171], v[228:231], v[22:25]
	v_mfma_f32_16x16x32_bf16 v[18:21], v[190:193], v[228:231], v[18:21]
	v_mfma_f32_16x16x32_bf16 v[6:9], v[168:171], v[236:239], v[6:9]
	v_mfma_f32_16x16x32_bf16 v[2:5], v[190:193], v[236:239], v[2:5]
	s_setprio 0
	s_barrier
	s_add_u32 s10, s10, 0x100
	s_addc_u32 s11, s11, 0
	s_add_u32 s47, s47, 0x100
	s_addc_u32 s48, s48, 0
	s_cmp_ge_u32 s49, s14
	s_mov_b32 s44, s49
	s_cbranch_scc0 .LBB0_88
